# barrier spin loops s_sleep 1 -> 12 (less polling traffic)
# speedup vs baseline: 1.0020x; 1.0020x over previous
.LBB0_97:
	s_sleep 12
	global_load_dword v2, v0, s[2:3] offset:32 sc1
	s_waitcnt vmcnt(0)
	v_and_b32_e32 v2, 0xffff0000, v2
	v_cmp_ne_u32_e32 vcc, v2, v1
	s_or_b64 s[4:5], vcc, s[4:5]
	s_andn2_b64 exec, exec, s[4:5]
	s_cbranch_execnz .LBB0_97

.LBB0_106:
	global_load_dword v15, v16, s[4:5] sc1
	s_waitcnt lgkmcnt(0)
	global_load_dword v0, v16, s[6:7] sc1
	global_load_dword v1, v16, s[8:9] sc1
	global_load_dword v2, v16, s[10:11] sc1
	global_load_dword v3, v16, s[12:13] sc1
	global_load_dword v4, v16, s[14:15] sc1
	global_load_dword v5, v16, s[16:17] sc1
	global_load_dword v6, v16, s[18:19] sc1
	global_load_dword v7, v16, s[20:21] sc1
	global_load_dword v8, v16, s[24:25] sc1
	global_load_dword v9, v16, s[34:35] sc1
	global_load_dword v10, v16, s[36:37] sc1
	global_load_dword v11, v16, s[38:39] sc1
	global_load_dword v12, v16, s[40:41] sc1
	global_load_dword v13, v16, s[42:43] sc1
	global_load_dword v14, v16, s[44:45] sc1
	s_mov_b64 s[46:47], -1
	s_mov_b64 s[48:49], -1
	s_waitcnt vmcnt(14)
	v_add_u32_e32 v17, v0, v15
	s_waitcnt vmcnt(13)
	v_add_u32_e32 v17, v17, v1
	s_waitcnt vmcnt(12)
	v_add_u32_e32 v17, v17, v2
	s_waitcnt vmcnt(11)
	v_add_u32_e32 v17, v17, v3
	s_waitcnt vmcnt(10)
	v_add_u32_e32 v17, v17, v4
	s_waitcnt vmcnt(9)
	v_add_u32_e32 v17, v17, v5
	s_waitcnt vmcnt(8)
	v_add_u32_e32 v17, v17, v6
	s_waitcnt vmcnt(7)
	v_add_u32_e32 v17, v17, v7
	s_waitcnt vmcnt(6)
	v_add_u32_e32 v17, v17, v8
	s_waitcnt vmcnt(5)
	v_add_u32_e32 v17, v17, v9
	s_waitcnt vmcnt(4)
	v_add_u32_e32 v17, v17, v10
	s_waitcnt vmcnt(3)
	v_add_u32_e32 v17, v17, v11
	s_waitcnt vmcnt(2)
	v_add_u32_e32 v17, v17, v12
	s_waitcnt vmcnt(1)
	v_add_u32_e32 v17, v17, v13
	s_waitcnt vmcnt(0)
	v_add_u32_e32 v17, v17, v14
	v_cmp_eq_u32_e32 vcc, s33, v17
	s_cbranch_vccnz .LBB0_105
	s_and_b32 s22, s52, 0xff
	s_cmp_eq_u32 s22, 0
	s_mov_b64 s[50:51], -1
	s_sleep 12
	s_cbranch_scc0 .LBB0_110
	global_load_dword v17, v16, s[2:3] sc1
	s_waitcnt vmcnt(0)
	v_cmp_eq_u32_e32 vcc, 0, v17
	s_cbranch_vccnz .LBB0_112
	s_mov_b64 s[50:51], 0

.LBB0_124:
	s_and_b32 s20, s33, 0xff
	s_mov_b64 s[18:19], -1
	s_cmp_lg_u32 s20, 0
	s_mov_b64 s[24:25], -1
	s_sleep 12
	s_cbranch_scc1 .LBB0_127
	global_load_dword v2, v0, s[10:11] sc1
	s_waitcnt vmcnt(0)
	v_cmp_eq_u32_e32 vcc, 0, v2
	s_cbranch_vccnz .LBB0_129
	s_mov_b64 s[24:25], 0
	s_mov_b64 s[20:21], -1

.LBB0_141:
	s_and_b32 s20, s33, 0xff
	s_cmp_lg_u32 s20, 0
	s_mov_b64 s[24:25], -1
	s_sleep 12
	s_cbranch_scc1 .LBB0_144
	global_load_dword v1, v0, s[12:13] sc1
	s_waitcnt vmcnt(0)
	v_cmp_eq_u32_e32 vcc, 0, v1
	s_cbranch_vccnz .LBB0_146
	s_mov_b64 s[24:25], 0
	s_mov_b64 s[20:21], -1

.LBB0_176:
	v_readlane_b32 s0, v253, 43
	v_readlane_b32 s1, v253, 44
	global_load_dword v9, v1, s[8:9] sc1
	s_waitcnt lgkmcnt(0)
	global_load_dword v0, v1, s[10:11] sc1
	global_load_dword v2, v1, s[12:13] sc1
	global_load_dword v3, v1, s[14:15] sc1
	global_load_dword v4, v1, s[6:7] sc1
	global_load_dword v5, v1, s[4:5] sc1
	global_load_dword v6, v1, s[62:63] sc1
	global_load_dword v7, v1, s[64:65] sc1
	global_load_dword v8, v1, s[48:49] sc1
	global_load_dword v10, v1, s[0:1] sc1
	v_readlane_b32 s0, v253, 45
	v_readlane_b32 s1, v253, 46
	s_mov_b64 s[36:37], -1
	s_mov_b64 s[38:39], -1
	s_waitcnt vmcnt(8)
	v_add_u32_e32 v17, v0, v9
	s_nop 0
	global_load_dword v11, v1, s[0:1] sc1
	v_readlane_b32 s0, v253, 26
	v_readlane_b32 s1, v253, 27
	s_waitcnt vmcnt(8)
	v_add_u32_e32 v17, v17, v2
	s_waitcnt vmcnt(7)
	v_add_u32_e32 v17, v17, v3
	s_waitcnt vmcnt(6)
	v_add_u32_e32 v17, v17, v4
	s_waitcnt vmcnt(5)
	v_add_u32_e32 v17, v17, v5
	s_waitcnt vmcnt(4)
	v_add_u32_e32 v17, v17, v6
	global_load_dword v12, v1, s[0:1] sc1
	v_readlane_b32 s0, v253, 28
	v_readlane_b32 s1, v253, 29
	s_waitcnt vmcnt(4)
	v_add_u32_e32 v17, v17, v7
	s_waitcnt vmcnt(3)
	v_add_u32_e32 v17, v17, v8
	s_waitcnt vmcnt(2)
	v_add_u32_e32 v17, v17, v10
	s_waitcnt vmcnt(1)
	v_add_u32_e32 v17, v17, v11
	global_load_dword v13, v1, s[0:1] sc1
	v_readlane_b32 s0, v253, 30
	v_readlane_b32 s1, v253, 31
	s_waitcnt vmcnt(1)
	v_add_u32_e32 v17, v17, v12
	s_nop 2
	global_load_dword v14, v1, s[0:1] sc1
	v_readlane_b32 s0, v253, 32
	v_readlane_b32 s1, v253, 33
	s_waitcnt vmcnt(1)
	v_add_u32_e32 v17, v17, v13
	s_nop 2
	global_load_dword v15, v1, s[0:1] sc1
	v_readlane_b32 s0, v253, 34
	v_readlane_b32 s1, v253, 35
	s_waitcnt vmcnt(1)
	v_add_u32_e32 v17, v17, v14
	s_nop 2
	global_load_dword v16, v1, s[0:1] sc1
	s_waitcnt vmcnt(1)
	v_add_u32_e32 v17, v17, v15
	s_waitcnt vmcnt(0)
	v_add_u32_e32 v17, v17, v16
	v_cmp_eq_u32_e32 vcc, s97, v17
	s_cbranch_vccnz .LBB0_175
	s_and_b32 s0, s2, 0xff
	s_cmp_eq_u32 s0, 0
	s_mov_b64 s[40:41], -1
	s_sleep 12
	s_cbranch_scc0 .LBB0_180
	global_load_dword v17, v1, s[50:51] sc1
	s_waitcnt vmcnt(0)
	v_cmp_eq_u32_e32 vcc, 0, v17
	s_cbranch_vccnz .LBB0_182
	s_mov_b64 s[40:41], 0

.LBB0_192:
	s_and_b32 s1, s0, 0xff
	s_mov_b64 s[44:45], -1
	s_cmp_lg_u32 s1, 0
	s_mov_b64 s[52:53], -1
	s_sleep 12
	s_cbranch_scc1 .LBB0_195
	global_load_dword v0, v1, s[50:51] sc1
	s_waitcnt vmcnt(0)
	v_cmp_eq_u32_e32 vcc, 0, v0
	s_cbranch_vccnz .LBB0_197
	s_mov_b64 s[52:53], 0
	s_mov_b64 s[46:47], -1

.LBB0_249:
	v_readlane_b32 s0, v253, 43
	v_readlane_b32 s1, v253, 44
	global_load_dword v9, v1, s[8:9] sc1
	global_load_dword v0, v1, s[10:11] sc1
	s_waitcnt lgkmcnt(0)
	global_load_dword v2, v1, s[12:13] sc1
	global_load_dword v3, v1, s[14:15] sc1
	global_load_dword v4, v1, s[6:7] sc1
	global_load_dword v5, v1, s[4:5] sc1
	global_load_dword v6, v1, s[62:63] sc1
	global_load_dword v7, v1, s[64:65] sc1
	global_load_dword v8, v1, s[48:49] sc1
	global_load_dword v10, v1, s[0:1] sc1
	v_readlane_b32 s0, v253, 45
	v_readlane_b32 s1, v253, 46
	s_mov_b64 s[36:37], -1
	s_mov_b64 s[38:39], -1
	s_waitcnt vmcnt(8)
	v_add_u32_e32 v17, v0, v9
	s_nop 0
	global_load_dword v11, v1, s[0:1] sc1
	v_readlane_b32 s0, v253, 26
	v_readlane_b32 s1, v253, 27
	s_waitcnt vmcnt(8)
	v_add_u32_e32 v17, v17, v2
	s_waitcnt vmcnt(7)
	v_add_u32_e32 v17, v17, v3
	s_waitcnt vmcnt(6)
	v_add_u32_e32 v17, v17, v4
	s_waitcnt vmcnt(5)
	v_add_u32_e32 v17, v17, v5
	s_waitcnt vmcnt(4)
	v_add_u32_e32 v17, v17, v6
	global_load_dword v12, v1, s[0:1] sc1
	v_readlane_b32 s0, v253, 28
	v_readlane_b32 s1, v253, 29
	s_waitcnt vmcnt(4)
	v_add_u32_e32 v17, v17, v7
	s_waitcnt vmcnt(3)
	v_add_u32_e32 v17, v17, v8
	s_waitcnt vmcnt(2)
	v_add_u32_e32 v17, v17, v10
	s_waitcnt vmcnt(1)
	v_add_u32_e32 v17, v17, v11
	global_load_dword v13, v1, s[0:1] sc1
	v_readlane_b32 s0, v253, 30
	v_readlane_b32 s1, v253, 31
	s_waitcnt vmcnt(1)
	v_add_u32_e32 v17, v17, v12
	s_nop 2
	global_load_dword v14, v1, s[0:1] sc1
	v_readlane_b32 s0, v253, 32
	v_readlane_b32 s1, v253, 33
	s_waitcnt vmcnt(1)
	v_add_u32_e32 v17, v17, v13
	s_nop 2
	global_load_dword v15, v1, s[0:1] sc1
	v_readlane_b32 s0, v253, 34
	v_readlane_b32 s1, v253, 35
	s_waitcnt vmcnt(1)
	v_add_u32_e32 v17, v17, v14
	s_nop 2
	global_load_dword v16, v1, s[0:1] sc1
	s_waitcnt vmcnt(1)
	v_add_u32_e32 v17, v17, v15
	s_waitcnt vmcnt(0)
	v_add_u32_e32 v17, v17, v16
	v_cmp_eq_u32_e32 vcc, s97, v17
	s_cbranch_vccnz .LBB0_248
	s_and_b32 s0, s2, 0xff
	s_cmp_eq_u32 s0, 0
	s_mov_b64 s[40:41], -1
	s_sleep 12
	s_cbranch_scc0 .LBB0_253
	global_load_dword v17, v1, s[50:51] sc1
	s_waitcnt vmcnt(0)
	v_cmp_eq_u32_e32 vcc, 0, v17
	s_cbranch_vccnz .LBB0_255
	s_mov_b64 s[40:41], 0

.LBB0_265:
	s_and_b32 s1, s0, 0xff
	s_mov_b64 s[44:45], -1
	s_cmp_lg_u32 s1, 0
	s_mov_b64 s[52:53], -1
	s_sleep 12
	s_cbranch_scc1 .LBB0_268
	global_load_dword v2, v1, s[50:51] sc1
	s_waitcnt vmcnt(0)
	v_cmp_eq_u32_e32 vcc, 0, v2
	s_cbranch_vccnz .LBB0_270
	s_mov_b64 s[52:53], 0
	s_mov_b64 s[46:47], -1

.LBB0_388:
	v_readlane_b32 s0, v253, 43
	v_readlane_b32 s1, v253, 44
	global_load_dword v9, v1, s[8:9] sc1
	global_load_dword v0, v1, s[10:11] sc1
	s_waitcnt lgkmcnt(0)
	global_load_dword v2, v1, s[12:13] sc1
	global_load_dword v3, v1, s[14:15] sc1
	global_load_dword v4, v1, s[6:7] sc1
	global_load_dword v5, v1, s[4:5] sc1
	global_load_dword v6, v1, s[62:63] sc1
	global_load_dword v7, v1, s[64:65] sc1
	global_load_dword v8, v1, s[48:49] sc1
	global_load_dword v10, v1, s[0:1] sc1
	v_readlane_b32 s0, v253, 45
	v_readlane_b32 s1, v253, 46
	s_mov_b64 s[38:39], -1
	s_mov_b64 s[40:41], -1
	s_waitcnt vmcnt(8)
	v_add_u32_e32 v17, v0, v9
	s_nop 0
	global_load_dword v11, v1, s[0:1] sc1
	v_readlane_b32 s0, v253, 26
	v_readlane_b32 s1, v253, 27
	s_waitcnt vmcnt(8)
	v_add_u32_e32 v17, v17, v2
	s_waitcnt vmcnt(7)
	v_add_u32_e32 v17, v17, v3
	s_waitcnt vmcnt(6)
	v_add_u32_e32 v17, v17, v4
	s_waitcnt vmcnt(5)
	v_add_u32_e32 v17, v17, v5
	s_waitcnt vmcnt(4)
	v_add_u32_e32 v17, v17, v6
	global_load_dword v12, v1, s[0:1] sc1
	v_readlane_b32 s0, v253, 28
	v_readlane_b32 s1, v253, 29
	s_waitcnt vmcnt(4)
	v_add_u32_e32 v17, v17, v7
	s_waitcnt vmcnt(3)
	v_add_u32_e32 v17, v17, v8
	s_waitcnt vmcnt(2)
	v_add_u32_e32 v17, v17, v10
	s_waitcnt vmcnt(1)
	v_add_u32_e32 v17, v17, v11
	global_load_dword v13, v1, s[0:1] sc1
	v_readlane_b32 s0, v253, 30
	v_readlane_b32 s1, v253, 31
	s_waitcnt vmcnt(1)
	v_add_u32_e32 v17, v17, v12
	s_nop 2
	global_load_dword v14, v1, s[0:1] sc1
	v_readlane_b32 s0, v253, 32
	v_readlane_b32 s1, v253, 33
	s_waitcnt vmcnt(1)
	v_add_u32_e32 v17, v17, v13
	s_nop 2
	global_load_dword v15, v1, s[0:1] sc1
	v_readlane_b32 s0, v253, 34
	v_readlane_b32 s1, v253, 35
	s_waitcnt vmcnt(1)
	v_add_u32_e32 v17, v17, v14
	s_nop 2
	global_load_dword v16, v1, s[0:1] sc1
	s_waitcnt vmcnt(1)
	v_add_u32_e32 v17, v17, v15
	s_waitcnt vmcnt(0)
	v_add_u32_e32 v17, v17, v16
	v_cmp_eq_u32_e32 vcc, s97, v17
	s_cbranch_vccnz .LBB0_387
	s_and_b32 s0, s2, 0xff
	s_cmp_eq_u32 s0, 0
	s_mov_b64 s[42:43], -1
	s_sleep 12
	s_cbranch_scc0 .LBB0_392
	global_load_dword v17, v1, s[50:51] sc1
	s_waitcnt vmcnt(0)
	v_cmp_eq_u32_e32 vcc, 0, v17
	s_cbranch_vccnz .LBB0_394
	s_mov_b64 s[42:43], 0

.LBB0_404:
	s_and_b32 s1, s0, 0xff
	s_mov_b64 s[46:47], -1
	s_cmp_lg_u32 s1, 0
	s_mov_b64 s[56:57], -1
	s_sleep 12
	s_cbranch_scc1 .LBB0_407
	global_load_dword v2, v1, s[50:51] sc1
	s_waitcnt vmcnt(0)
	v_cmp_eq_u32_e32 vcc, 0, v2
	s_cbranch_vccnz .LBB0_409
	s_mov_b64 s[56:57], 0
	s_mov_b64 s[52:53], -1

.LBB0_899:
	v_readlane_b32 s0, v253, 43
	v_readlane_b32 s1, v253, 44
	global_load_dword v9, v1, s[8:9] sc1
	global_load_dword v0, v1, s[10:11] sc1
	s_waitcnt lgkmcnt(0)
	global_load_dword v2, v1, s[12:13] sc1
	global_load_dword v3, v1, s[14:15] sc1
	global_load_dword v4, v1, s[6:7] sc1
	global_load_dword v5, v1, s[4:5] sc1
	global_load_dword v6, v1, s[62:63] sc1
	global_load_dword v7, v1, s[64:65] sc1
	global_load_dword v8, v1, s[48:49] sc1
	global_load_dword v10, v1, s[0:1] sc1
	v_readlane_b32 s0, v253, 45
	v_readlane_b32 s1, v253, 46
	s_mov_b64 s[40:41], -1
	s_mov_b64 s[42:43], -1
	s_waitcnt vmcnt(8)
	v_add_u32_e32 v17, v0, v9
	s_nop 0
	global_load_dword v11, v1, s[0:1] sc1
	v_readlane_b32 s0, v253, 26
	v_readlane_b32 s1, v253, 27
	s_waitcnt vmcnt(8)
	v_add_u32_e32 v17, v17, v2
	s_waitcnt vmcnt(7)
	v_add_u32_e32 v17, v17, v3
	s_waitcnt vmcnt(6)
	v_add_u32_e32 v17, v17, v4
	s_waitcnt vmcnt(5)
	v_add_u32_e32 v17, v17, v5
	s_waitcnt vmcnt(4)
	v_add_u32_e32 v17, v17, v6
	global_load_dword v12, v1, s[0:1] sc1
	v_readlane_b32 s0, v253, 28
	v_readlane_b32 s1, v253, 29
	s_waitcnt vmcnt(4)
	v_add_u32_e32 v17, v17, v7
	s_waitcnt vmcnt(3)
	v_add_u32_e32 v17, v17, v8
	s_waitcnt vmcnt(2)
	v_add_u32_e32 v17, v17, v10
	s_waitcnt vmcnt(1)
	v_add_u32_e32 v17, v17, v11
	global_load_dword v13, v1, s[0:1] sc1
	v_readlane_b32 s0, v253, 30
	v_readlane_b32 s1, v253, 31
	s_waitcnt vmcnt(1)
	v_add_u32_e32 v17, v17, v12
	s_nop 2
	global_load_dword v14, v1, s[0:1] sc1
	v_readlane_b32 s0, v253, 32
	v_readlane_b32 s1, v253, 33
	s_waitcnt vmcnt(1)
	v_add_u32_e32 v17, v17, v13
	s_nop 2
	global_load_dword v15, v1, s[0:1] sc1
	v_readlane_b32 s0, v253, 34
	v_readlane_b32 s1, v253, 35
	s_waitcnt vmcnt(1)
	v_add_u32_e32 v17, v17, v14
	s_nop 2
	global_load_dword v16, v1, s[0:1] sc1
	s_waitcnt vmcnt(1)
	v_add_u32_e32 v17, v17, v15
	s_waitcnt vmcnt(0)
	v_add_u32_e32 v17, v17, v16
	v_cmp_eq_u32_e32 vcc, s97, v17
	s_cbranch_vccnz .LBB0_898
	s_and_b32 s0, s2, 0xff
	s_cmp_eq_u32 s0, 0
	s_mov_b64 s[44:45], -1
	s_sleep 12
	s_cbranch_scc0 .LBB0_903
	global_load_dword v17, v1, s[50:51] sc1
	s_waitcnt vmcnt(0)
	v_cmp_eq_u32_e32 vcc, 0, v17
	s_cbranch_vccnz .LBB0_905
	s_mov_b64 s[44:45], 0

.LBB0_915:
	s_and_b32 s1, s0, 0xff
	s_mov_b64 s[52:53], -1
	s_cmp_lg_u32 s1, 0
	s_mov_b64 s[64:65], -1
	s_sleep 12
	s_cbranch_scc1 .LBB0_918
	global_load_dword v2, v1, s[50:51] sc1
	s_waitcnt vmcnt(0)
	v_cmp_eq_u32_e32 vcc, 0, v2
	s_cbranch_vccnz .LBB0_920
	s_mov_b64 s[64:65], 0
	s_mov_b64 s[56:57], -1
